# S1: DSA QK^T pipelining + DSA unit = own indexer unit, grid barrier between those phases removed (all other barriers global as in baseline)
# baseline (speedup 1.0000x reference)
; #define LAS __attribute__((address_space(3)))
; DEVI int otid() { int t = threadIdx.x; asm volatile("" : "+v"(t)); return t; }
; DEVI void dsa_phase(LAS unsigned char* lds, const bf16_t* EV, const float* SC, bf16_t* O) {
;     const int tid = otid(), wid = tid >> 6, lane = tid & 63;
;     LAS u64* maskl = (LAS u64*)(lds + OFF_MASK);
;     for (int u = blockIdx.x; u < NB * 64; u += gridDim.x) {
;         const int g = 63 - (u & 63), b = u >> 6, t0 = 32 * g, m0 = b * SEQ + t0, c = g >> 1;
; #pragma unroll 1
;         for (int rr = 0; rr < 4; ++rr) { const int row = 4 * wid + rr; select_row(SC + (size_t)(m0 + row) * SEQ, c, maskl + row * 32, lane); }
;         asm volatile("s_waitcnt lgkmcnt(0)" ::: "memory"); __builtin_amdgcn_s_barrier(); asm volatile("" ::: "memory");
;         attn_unit<M_DSA>(lds, EV + (size_t)m0 * EVP + EV_QA + wid * HD, EVP, EV + (size_t)(b * SEQ) * EVP + EV_KA, EV + (size_t)(b * SEQ) * EVP + EV_VA, EVP,
;                          O + (size_t)m0 * DM + wid * HD, DM, 0, c + 1, 1, 0, 1 << 30, t0);
.LBB11_1358:
	v_readlane_b32 s1, v249, 40
	s_mov_b64 s[2:3], 0
	v_and_b32_e32 v1, 63, v0
	v_readlane_b32 s4, v251, 16
	v_readlane_b32 s5, v251, 17
	v_mov_b32_e32 v1, v0
	s_andn2_b64 vcc, exec, s[4:5]
	s_cbranch_vccnz .LBB11_1665
	v_readlane_b32 s4, v249, 17
	v_mov_b64_e32 v[4:5], s[2:3]
	v_readlane_b32 s18, v249, 31
	v_readlane_b32 s19, v249, 32
	s_mov_b64 s[2:3], 0x53200000
	v_and_b32_e32 v154, 63, v1
	v_lshl_add_u64 v[148:149], s[18:19], 0, v[4:5]
	v_lshl_add_u64 v[150:151], v[148:149], 0, s[2:3]
	s_mov_b64 s[2:3], 0x5ce00000
	v_ashrrev_i32_e32 v1, 6, v1
	v_lshl_add_u64 v[152:153], v[148:149], 0, s[2:3]
	v_cmp_ne_u32_e64 s[2:3], 0, v154
	v_lshlrev_b32_e32 v4, 7, v1
	v_ashrrev_i32_e32 v5, 31, v4
	v_writelane_b32 v252, s2, 27
	v_lshlrev_b64 v[4:5], 1, v[4:5]
	v_readlane_b32 s1, v249, 0
	v_writelane_b32 v252, s3, 28
	v_readlane_b32 s9, v249, 22
	v_lshl_add_u64 v[156:157], v[150:151], 0, v[4:5]
	v_lshl_add_u64 v[4:5], v[148:149], 0, v[4:5]
	s_mov_b64 s[2:3], 0x59200000
	v_writelane_b32 v252, s1, 29
	v_readlane_b32 s1, v251, 61
	v_lshlrev_b32_e32 v155, 2, v1
	v_cmp_eq_u32_e64 s[36:37], 0, v154
	v_lshl_add_u64 v[158:159], v[4:5], 0, s[2:3]
	v_lshlrev_b32_e32 v2, 2, v154
	v_readlane_b32 s9, v251, 59
	s_xor_b32 s9, s9, 0x7e0
	s_mov_b32 s3, s1
	v_readlane_b32 s5, v249, 18
	v_readlane_b32 s6, v249, 19
	v_readlane_b32 s7, v249, 20
	v_readlane_b32 s8, v249, 21
	v_readlane_b32 s10, v249, 23
	v_readlane_b32 s11, v249, 24
	v_readlane_b32 s12, v249, 25
	v_readlane_b32 s13, v249, 26
	v_readlane_b32 s14, v249, 27
	v_readlane_b32 s15, v249, 28
	v_readlane_b32 s16, v249, 29
	v_readlane_b32 s17, v249, 30
	s_branch .LBB11_1361
